# v17 + gate/up epilogue: the leading half computes its g*u products before the epilogue-align barrier (barrier moved 32 instructions later)
# speedup vs baseline: 1.0070x; 1.0070x over previous
; #define PG8_STAGE(bufoff, gbase, voff) do { _Pragma("unroll") for (int _i = 0; _i < 2; ++_i) \
;         __builtin_amdgcn_global_load_lds((const unsigned*)((const char*)(gbase) + (voff)[_i]), (PG8_LAS unsigned*)(lds + (bufoff) + ldsw + _i * 8192), 16, 0, 0); } while (0)
; #define PG8_LDA(dst, b, h) do { _Pragma("unroll") for (int m = 0; m < 4; ++m) _Pragma("unroll") for (int k = 0; k < 2; ++k) dst[m][k] = *(const PG8_LAS bf16x8*)(lds + PG8_SA(b, h) + aoff + m * 2048 + k * 1024); } while (0)
; #define PG8_LDB(dst, b, h) do { _Pragma("unroll") for (int n = 0; n < 2; ++n) _Pragma("unroll") for (int k = 0; k < 2; ++k) dst[n][k] = *(const PG8_LAS bf16x8*)(lds + PG8_SB(b, h) + boff + n * 2048 + k * 1024); } while (0)
; #define PG8_MMA(ai, bj, At, Bt) do { __builtin_amdgcn_s_setprio(1); _Pragma("unroll") for (int m = 0; m < 4; ++m) _Pragma("unroll") for (int n = 0; n < 2; ++n) _Pragma("unroll") for (int k = 0; k < 2; ++k) \
;         acc[ai][bj][m][n] = __builtin_amdgcn_mfma_f32_16x16x32_bf16(Bt[n][k], At[m][k], acc[ai][bj][m][n], 0, 0, 0); __builtin_amdgcn_s_setprio(0); } while (0)
; #define PG8_WAIT_V(n) asm volatile("s_waitcnt vmcnt(" #n ")" ::: "memory")
; #define PG8_WAIT_L(n) asm volatile("s_waitcnt lgkmcnt(" #n ")" ::: "memory")
; #define PG8_BAR __builtin_amdgcn_s_barrier()
; #define PG8_SCHED __builtin_amdgcn_sched_barrier(0)
; template <class Epi, class Sched, bool ALIGN_EPI = false, bool SP2 = false>
; __device__ __forceinline__ void gemm_phase(PG8_LAS unsigned char* lds, const Gemm g, const Sched& S, const Epi& E) {
;     ...
;             PG8_LDB(B0, 0, 0); PG8_LDB(B1, 0, 1); PG8_SCHED; PG8_LDA(At, 0, 0); PG8_STAGE(PG8_SA(1, 1), a1 + hstep, voffA);
;             PG8_WAIT_V(8); PG8_WAIT_L(0); PG8_BAR; PG8_MMA(0, 0, At, B0); PG8_MMA(0, 1, At, B1); PG8_BAR; PG8_SCHED;
;             PG8_LDA(At, 0, 1); PG8_STAGE(PG8_SB(0, 0), b2, voffB); PG8_STAGE(PG8_SB(0, 1), b2 + hstep, voffB); PG8_STAGE(PG8_SA(0, 0), a2, voffA);
;             PG8_WAIT_V(8); PG8_WAIT_L(0); PG8_BAR; PG8_MMA(1, 0, At, B0); PG8_MMA(1, 1, At, B1); PG8_BAR; PG8_SCHED;
;             PG8_LDB(B0, 1, 0); PG8_LDB(B1, 1, 1); PG8_SCHED; PG8_LDA(At, 1, 0); PG8_STAGE(PG8_SA(0, 1), a2 + hstep, voffA);
;             PG8_WAIT_V(8); PG8_WAIT_L(0); PG8_BAR; PG8_MMA(0, 0, At, B0); PG8_MMA(0, 1, At, B1); PG8_BAR; PG8_SCHED;
.LBB0_493:
	s_add_u32 s24, s22, 0xfffc0080
	s_addc_u32 s25, s23, -1
	s_add_i32 s51, 0, 0x10000
	s_cmp_eq_u32 s50, 12
	s_cselect_b32 s27, s17, s25
	s_cselect_b32 s26, s46, s24
	v_add_u32_e32 v146, s51, v149
	s_cselect_b32 s25, s15, s49
	s_cselect_b32 s24, s47, s48
	s_add_i32 s54, 0, 0x14000
	ds_read_b128 v[142:145], v146
	ds_read_b128 v[152:155], v146 offset:1024
	ds_read_b128 v[172:175], v146 offset:2048
	ds_read_b128 v[176:179], v146 offset:3072
	v_add_u32_e32 v146, s54, v149
	ds_read_b128 v[180:183], v146
	ds_read_b128 v[184:187], v146 offset:1024
	ds_read_b128 v[188:191], v146 offset:2048
	ds_read_b128 v[192:195], v146 offset:3072
	s_add_i32 m0, s30, 0xc000
	ds_read_b128 v[196:199], v151
	ds_read_b128 v[214:217], v151 offset:1024
	ds_read_b128 v[218:221], v151 offset:2048
	ds_read_b128 v[222:225], v151 offset:3072
	ds_read_b128 v[226:229], v151 offset:4096
	ds_read_b128 v[230:233], v151 offset:5120
	ds_read_b128 v[234:237], v151 offset:6144
	ds_read_b128 v[238:241], v151 offset:7168
	global_load_lds_dwordx4 v138, s[22:23]
	s_add_i32 m0, s30, 0xe000
	s_nop 0
	global_load_lds_dwordx4 v140, s[22:23]
	s_waitcnt vmcnt(8)
	s_waitcnt lgkmcnt(0)
	s_barrier
	s_setprio 1
	s_waitcnt lgkmcnt(0)
	v_mfma_f32_16x16x32_bf16 v[126:129], v[142:145], v[196:199], v[126:129]
	v_mfma_f32_16x16x32_bf16 v[118:121], v[172:175], v[196:199], v[118:121]
	v_mfma_f32_16x16x32_bf16 v[110:113], v[142:145], v[218:221], v[110:113]
	v_mfma_f32_16x16x32_bf16 v[102:105], v[172:175], v[218:221], v[102:105]
	v_mfma_f32_16x16x32_bf16 v[94:97], v[142:145], v[226:229], v[94:97]
	v_mfma_f32_16x16x32_bf16 v[86:89], v[172:175], v[226:229], v[86:89]
	v_mfma_f32_16x16x32_bf16 v[78:81], v[142:145], v[234:237], v[78:81]
	v_mfma_f32_16x16x32_bf16 v[70:73], v[172:175], v[234:237], v[70:73]
	v_mfma_f32_16x16x32_bf16 v[126:129], v[152:155], v[214:217], v[126:129]
	v_mfma_f32_16x16x32_bf16 v[118:121], v[176:179], v[214:217], v[118:121]
	v_mfma_f32_16x16x32_bf16 v[110:113], v[152:155], v[222:225], v[110:113]
	v_mfma_f32_16x16x32_bf16 v[102:105], v[176:179], v[222:225], v[102:105]
	v_mfma_f32_16x16x32_bf16 v[94:97], v[152:155], v[230:233], v[94:97]
	v_mfma_f32_16x16x32_bf16 v[86:89], v[176:179], v[230:233], v[86:89]
	v_mfma_f32_16x16x32_bf16 v[78:81], v[152:155], v[238:241], v[78:81]
	v_mfma_f32_16x16x32_bf16 v[70:73], v[176:179], v[238:241], v[70:73]
	s_setprio 0
	s_setprio 1
	v_mfma_f32_16x16x32_bf16 v[122:125], v[180:183], v[196:199], v[122:125]
	v_mfma_f32_16x16x32_bf16 v[114:117], v[188:191], v[196:199], v[114:117]
	v_mfma_f32_16x16x32_bf16 v[106:109], v[180:183], v[218:221], v[106:109]
	v_mfma_f32_16x16x32_bf16 v[98:101], v[188:191], v[218:221], v[98:101]
	v_mfma_f32_16x16x32_bf16 v[90:93], v[180:183], v[226:229], v[90:93]
	v_mfma_f32_16x16x32_bf16 v[82:85], v[188:191], v[226:229], v[82:85]
	v_mfma_f32_16x16x32_bf16 v[74:77], v[180:183], v[234:237], v[74:77]
	v_mfma_f32_16x16x32_bf16 v[66:69], v[188:191], v[234:237], v[66:69]
	v_mfma_f32_16x16x32_bf16 v[122:125], v[184:187], v[214:217], v[122:125]
	v_mfma_f32_16x16x32_bf16 v[114:117], v[192:195], v[214:217], v[114:117]
	v_mfma_f32_16x16x32_bf16 v[106:109], v[184:187], v[222:225], v[106:109]
	v_mfma_f32_16x16x32_bf16 v[98:101], v[192:195], v[222:225], v[98:101]
	v_mfma_f32_16x16x32_bf16 v[90:93], v[184:187], v[230:233], v[90:93]
	v_mfma_f32_16x16x32_bf16 v[82:85], v[192:195], v[230:233], v[82:85]
	v_mfma_f32_16x16x32_bf16 v[74:77], v[184:187], v[238:241], v[74:77]
	v_mfma_f32_16x16x32_bf16 v[66:69], v[192:195], v[238:241], v[66:69]
	s_setprio 0
	s_barrier
	s_add_i32 s51, s51, s2
	s_mov_b32 m0, s51
	ds_read_b128 v[196:199], v151 offset:16384
	ds_read_b128 v[214:217], v151 offset:17408
	ds_read_b128 v[218:221], v151 offset:18432
	ds_read_b128 v[222:225], v151 offset:19456
	ds_read_b128 v[226:229], v151 offset:20480
	ds_read_b128 v[230:233], v151 offset:21504
	ds_read_b128 v[234:237], v151 offset:22528
	ds_read_b128 v[238:241], v151 offset:23552
	global_load_lds_dwordx4 v0, s[24:25]
	s_add_i32 m0, s51, 0x2000
	s_add_u32 s52, s24, 0x40000
	s_addc_u32 s53, s25, 0
	s_add_i32 s51, s54, s2
	global_load_lds_dwordx4 v130, s[24:25]
	s_mov_b32 m0, s51
	s_nop 0
	global_load_lds_dwordx4 v0, s[52:53]
	s_add_i32 m0, s51, 0x2000
	s_nop 0
	global_load_lds_dwordx4 v130, s[52:53]
	s_mov_b32 m0, s30
	s_nop 0
	global_load_lds_dwordx4 v134, s[26:27]
	s_mov_b32 m0, s31
	s_nop 0
	global_load_lds_dwordx4 v132, s[26:27]
	s_waitcnt vmcnt(8)
	s_waitcnt lgkmcnt(0)
	s_barrier
	s_setprio 1
	s_waitcnt lgkmcnt(0)
	v_mfma_f32_16x16x32_bf16 v[62:65], v[142:145], v[196:199], v[62:65]
	v_mfma_f32_16x16x32_bf16 v[54:57], v[172:175], v[196:199], v[54:57]
	v_mfma_f32_16x16x32_bf16 v[46:49], v[142:145], v[218:221], v[46:49]
	v_mfma_f32_16x16x32_bf16 v[38:41], v[172:175], v[218:221], v[38:41]
	v_mfma_f32_16x16x32_bf16 v[30:33], v[142:145], v[226:229], v[30:33]
	v_mfma_f32_16x16x32_bf16 v[22:25], v[172:175], v[226:229], v[22:25]
	v_mfma_f32_16x16x32_bf16 v[14:17], v[142:145], v[234:237], v[14:17]
	v_mfma_f32_16x16x32_bf16 v[6:9], v[172:175], v[234:237], v[6:9]
	v_mfma_f32_16x16x32_bf16 v[62:65], v[152:155], v[214:217], v[62:65]
	v_mfma_f32_16x16x32_bf16 v[54:57], v[176:179], v[214:217], v[54:57]
	v_mfma_f32_16x16x32_bf16 v[46:49], v[152:155], v[222:225], v[46:49]
	v_mfma_f32_16x16x32_bf16 v[38:41], v[176:179], v[222:225], v[38:41]
	v_mfma_f32_16x16x32_bf16 v[30:33], v[152:155], v[230:233], v[30:33]
	v_mfma_f32_16x16x32_bf16 v[22:25], v[176:179], v[230:233], v[22:25]
	v_mfma_f32_16x16x32_bf16 v[14:17], v[152:155], v[238:241], v[14:17]
	v_mfma_f32_16x16x32_bf16 v[6:9], v[176:179], v[238:241], v[6:9]
	s_setprio 0
	s_setprio 1
	v_mfma_f32_16x16x32_bf16 v[58:61], v[180:183], v[196:199], v[58:61]
	v_mfma_f32_16x16x32_bf16 v[50:53], v[188:191], v[196:199], v[50:53]
	v_mfma_f32_16x16x32_bf16 v[42:45], v[180:183], v[218:221], v[42:45]
	v_mfma_f32_16x16x32_bf16 v[34:37], v[188:191], v[218:221], v[34:37]
	v_mfma_f32_16x16x32_bf16 v[26:29], v[180:183], v[226:229], v[26:29]
	v_mfma_f32_16x16x32_bf16 v[18:21], v[188:191], v[226:229], v[18:21]
	v_mfma_f32_16x16x32_bf16 v[10:13], v[180:183], v[234:237], v[10:13]
	v_mfma_f32_16x16x32_bf16 v[2:5], v[188:191], v[234:237], v[2:5]
	v_mfma_f32_16x16x32_bf16 v[58:61], v[184:187], v[214:217], v[58:61]
	v_mfma_f32_16x16x32_bf16 v[50:53], v[192:195], v[214:217], v[50:53]
	v_mfma_f32_16x16x32_bf16 v[42:45], v[184:187], v[222:225], v[42:45]
	v_mfma_f32_16x16x32_bf16 v[34:37], v[192:195], v[222:225], v[34:37]
	v_mfma_f32_16x16x32_bf16 v[26:29], v[184:187], v[230:233], v[26:29]
	v_mfma_f32_16x16x32_bf16 v[18:21], v[192:195], v[230:233], v[18:21]
	v_mfma_f32_16x16x32_bf16 v[10:13], v[184:187], v[238:241], v[10:13]
	v_mfma_f32_16x16x32_bf16 v[2:5], v[192:195], v[238:241], v[2:5]
	s_setprio 0
	s_barrier
; #define PG8_STAGE(bufoff, gbase, voff) do { _Pragma("unroll") for (int _i = 0; _i < 2; ++_i) \
;         __builtin_amdgcn_global_load_lds((const unsigned*)((const char*)(gbase) + (voff)[_i]), (PG8_LAS unsigned*)(lds + (bufoff) + ldsw + _i * 8192), 16, 0, 0); } while (0)
; #define PG8_LDA(dst, b, h) do { _Pragma("unroll") for (int m = 0; m < 4; ++m) _Pragma("unroll") for (int k = 0; k < 2; ++k) dst[m][k] = *(const PG8_LAS bf16x8*)(lds + PG8_SA(b, h) + aoff + m * 2048 + k * 1024); } while (0)
; #define PG8_LDB(dst, b, h) do { _Pragma("unroll") for (int n = 0; n < 2; ++n) _Pragma("unroll") for (int k = 0; k < 2; ++k) dst[n][k] = *(const PG8_LAS bf16x8*)(lds + PG8_SB(b, h) + boff + n * 2048 + k * 1024); } while (0)
; #define PG8_MMA(ai, bj, At, Bt) do { __builtin_amdgcn_s_setprio(1); _Pragma("unroll") for (int m = 0; m < 4; ++m) _Pragma("unroll") for (int n = 0; n < 2; ++n) _Pragma("unroll") for (int k = 0; k < 2; ++k) \
;         acc[ai][bj][m][n] = __builtin_amdgcn_mfma_f32_16x16x32_bf16(Bt[n][k], At[m][k], acc[ai][bj][m][n], 0, 0, 0); __builtin_amdgcn_s_setprio(0); } while (0)
; #define PG8_WAIT_V(n) asm volatile("s_waitcnt vmcnt(" #n ")" ::: "memory")
; #define PG8_WAIT_L(n) asm volatile("s_waitcnt lgkmcnt(" #n ")" ::: "memory")
; #define PG8_BAR __builtin_amdgcn_s_barrier()
; #define PG8_SCHED __builtin_amdgcn_sched_barrier(0)
; template <class Epi, class Sched, bool ALIGN_EPI = false, bool SP2 = false>
; __device__ __forceinline__ void gemm_phase(PG8_LAS unsigned char* lds, const Gemm g, const Sched& S, const Epi& E) {
;     ...
;             PG8_LDB(B0, 1, 0); PG8_LDB(B1, 1, 1); PG8_SCHED; PG8_LDA(At, 1, 0); PG8_STAGE(PG8_SA(0, 1), a2 + hstep, voffA);
;             PG8_WAIT_V(8); PG8_WAIT_L(0); PG8_BAR; PG8_MMA(0, 0, At, B0); PG8_MMA(0, 1, At, B1); PG8_BAR; PG8_SCHED;
;             PG8_LDA(At, 1, 1); PG8_STAGE(PG8_SB(1, 0), b3, voffB); PG8_STAGE(PG8_SB(1, 1), b3 + hstep, voffB); PG8_STAGE(PG8_SA(1, 0), a3, voffA);
;             PG8_WAIT_V(8); PG8_WAIT_L(0); PG8_BAR; PG8_MMA(1, 0, At, B0); PG8_MMA(1, 1, At, B1); PG8_BAR; PG8_SCHED;
	s_add_i32 s51, 0, 0x18000
	v_add_u32_e32 v158, s51, v149
	s_add_i32 s52, 0, 0x1c000
	ds_read_b128 v[142:145], v158
	ds_read_b128 v[152:155], v158 offset:1024
	ds_read_b128 v[172:175], v158 offset:2048
	ds_read_b128 v[176:179], v158 offset:3072
	v_add_u32_e32 v158, s52, v149
	ds_read_b128 v[180:183], v158
	ds_read_b128 v[184:187], v158 offset:1024
	ds_read_b128 v[188:191], v158 offset:2048
	ds_read_b128 v[192:195], v158 offset:3072
	s_add_u32 s26, s26, 0x40000
	s_addc_u32 s27, s27, 0
	s_mov_b32 m0, s34
	ds_read_b128 v[196:199], v151 offset:32768
	ds_read_b128 v[214:217], v151 offset:33792
	ds_read_b128 v[218:221], v151 offset:34816
	ds_read_b128 v[222:225], v151 offset:35840
	ds_read_b128 v[226:229], v151 offset:36864
	ds_read_b128 v[230:233], v151 offset:37888
	ds_read_b128 v[234:237], v151 offset:38912
	ds_read_b128 v[238:241], v151 offset:39936
	global_load_lds_dwordx4 v134, s[26:27]
	s_mov_b32 m0, s35
	s_nop 0
	global_load_lds_dwordx4 v132, s[26:27]
	s_waitcnt vmcnt(8)
	s_waitcnt lgkmcnt(0)
	s_barrier
	s_setprio 1
	s_waitcnt lgkmcnt(0)
	v_mfma_f32_16x16x32_bf16 v[126:129], v[142:145], v[196:199], v[126:129]
	v_mfma_f32_16x16x32_bf16 v[118:121], v[172:175], v[196:199], v[118:121]
	v_mfma_f32_16x16x32_bf16 v[110:113], v[142:145], v[218:221], v[110:113]
	v_mfma_f32_16x16x32_bf16 v[102:105], v[172:175], v[218:221], v[102:105]
	v_mfma_f32_16x16x32_bf16 v[94:97], v[142:145], v[226:229], v[94:97]
	v_mfma_f32_16x16x32_bf16 v[86:89], v[172:175], v[226:229], v[86:89]
	v_mfma_f32_16x16x32_bf16 v[78:81], v[142:145], v[234:237], v[78:81]
	v_mfma_f32_16x16x32_bf16 v[70:73], v[172:175], v[234:237], v[70:73]
	v_mfma_f32_16x16x32_bf16 v[126:129], v[152:155], v[214:217], v[126:129]
	v_mfma_f32_16x16x32_bf16 v[118:121], v[176:179], v[214:217], v[118:121]
	v_mfma_f32_16x16x32_bf16 v[110:113], v[152:155], v[222:225], v[110:113]
	v_mfma_f32_16x16x32_bf16 v[102:105], v[176:179], v[222:225], v[102:105]
	v_mfma_f32_16x16x32_bf16 v[94:97], v[152:155], v[230:233], v[94:97]
	v_mfma_f32_16x16x32_bf16 v[86:89], v[176:179], v[230:233], v[86:89]
	v_mfma_f32_16x16x32_bf16 v[78:81], v[152:155], v[238:241], v[78:81]
	v_mfma_f32_16x16x32_bf16 v[70:73], v[176:179], v[238:241], v[70:73]
	s_setprio 0
	s_setprio 1
	v_mfma_f32_16x16x32_bf16 v[122:125], v[180:183], v[196:199], v[122:125]
	v_mfma_f32_16x16x32_bf16 v[114:117], v[188:191], v[196:199], v[114:117]
	v_mfma_f32_16x16x32_bf16 v[106:109], v[180:183], v[218:221], v[106:109]
	v_mfma_f32_16x16x32_bf16 v[98:101], v[188:191], v[218:221], v[98:101]
	v_mfma_f32_16x16x32_bf16 v[90:93], v[180:183], v[226:229], v[90:93]
	v_mfma_f32_16x16x32_bf16 v[82:85], v[188:191], v[226:229], v[82:85]
	v_mfma_f32_16x16x32_bf16 v[74:77], v[180:183], v[234:237], v[74:77]
	v_mfma_f32_16x16x32_bf16 v[66:69], v[188:191], v[234:237], v[66:69]
	v_mfma_f32_16x16x32_bf16 v[122:125], v[184:187], v[214:217], v[122:125]
	v_mfma_f32_16x16x32_bf16 v[114:117], v[192:195], v[214:217], v[114:117]
	v_mfma_f32_16x16x32_bf16 v[106:109], v[184:187], v[222:225], v[106:109]
	v_mfma_f32_16x16x32_bf16 v[98:101], v[192:195], v[222:225], v[98:101]
	v_mfma_f32_16x16x32_bf16 v[90:93], v[184:187], v[230:233], v[90:93]
	v_mfma_f32_16x16x32_bf16 v[82:85], v[192:195], v[230:233], v[82:85]
	v_mfma_f32_16x16x32_bf16 v[74:77], v[184:187], v[238:241], v[74:77]
	v_mfma_f32_16x16x32_bf16 v[66:69], v[192:195], v[238:241], v[66:69]
	s_setprio 0
	s_barrier
	s_add_u32 s98, s26, 0xfffc0080
	s_addc_u32 s99, s27, -1
	s_add_i32 s26, s51, s2
	s_add_u32 s100, s24, 0x80
	s_addc_u32 s101, s25, 0
	s_mov_b32 m0, s26
	ds_read_b128 v[196:199], v151 offset:49152
	ds_read_b128 v[214:217], v151 offset:50176
	ds_read_b128 v[218:221], v151 offset:51200
	ds_read_b128 v[222:225], v151 offset:52224
	ds_read_b128 v[226:229], v151 offset:53248
	ds_read_b128 v[230:233], v151 offset:54272
	ds_read_b128 v[234:237], v151 offset:55296
	ds_read_b128 v[238:241], v151 offset:56320
	global_load_lds_dwordx4 v0, s[100:101]
	s_add_i32 m0, s26, 0x2000
	s_add_u32 s24, s24, 0x40080
	s_addc_u32 s25, s25, 0
	s_add_i32 s26, s52, s2
	global_load_lds_dwordx4 v130, s[100:101]
	s_mov_b32 m0, s26
	s_nop 0
	global_load_lds_dwordx4 v0, s[24:25]
	s_add_i32 m0, s26, 0x2000
	s_nop 0
	global_load_lds_dwordx4 v130, s[24:25]
	s_mov_b32 m0, s37
	s_nop 0
	global_load_lds_dwordx4 v134, s[98:99]
	s_mov_b32 m0, s38
	s_nop 0
	global_load_lds_dwordx4 v132, s[98:99]
	s_waitcnt vmcnt(8)
	s_waitcnt lgkmcnt(0)
	s_barrier
	s_setprio 1
	s_waitcnt lgkmcnt(0)
	v_mfma_f32_16x16x32_bf16 v[62:65], v[142:145], v[196:199], v[62:65]
	v_mfma_f32_16x16x32_bf16 v[54:57], v[172:175], v[196:199], v[54:57]
	v_mfma_f32_16x16x32_bf16 v[46:49], v[142:145], v[218:221], v[46:49]
	v_mfma_f32_16x16x32_bf16 v[38:41], v[172:175], v[218:221], v[38:41]
	v_mfma_f32_16x16x32_bf16 v[30:33], v[142:145], v[226:229], v[30:33]
	v_mfma_f32_16x16x32_bf16 v[22:25], v[172:175], v[226:229], v[22:25]
	v_mfma_f32_16x16x32_bf16 v[14:17], v[142:145], v[234:237], v[14:17]
	v_mfma_f32_16x16x32_bf16 v[6:9], v[172:175], v[234:237], v[6:9]
	v_mfma_f32_16x16x32_bf16 v[62:65], v[152:155], v[214:217], v[62:65]
	v_mfma_f32_16x16x32_bf16 v[54:57], v[176:179], v[214:217], v[54:57]
	v_mfma_f32_16x16x32_bf16 v[46:49], v[152:155], v[222:225], v[46:49]
	v_mfma_f32_16x16x32_bf16 v[38:41], v[176:179], v[222:225], v[38:41]
	v_mfma_f32_16x16x32_bf16 v[30:33], v[152:155], v[230:233], v[30:33]
	v_mfma_f32_16x16x32_bf16 v[22:25], v[176:179], v[230:233], v[22:25]
	v_mfma_f32_16x16x32_bf16 v[14:17], v[152:155], v[238:241], v[14:17]
	v_mfma_f32_16x16x32_bf16 v[6:9], v[176:179], v[238:241], v[6:9]
	s_setprio 0
	s_setprio 1
	v_mfma_f32_16x16x32_bf16 v[58:61], v[180:183], v[196:199], v[58:61]
	v_mfma_f32_16x16x32_bf16 v[50:53], v[188:191], v[196:199], v[50:53]
	v_mfma_f32_16x16x32_bf16 v[42:45], v[180:183], v[218:221], v[42:45]
	v_mfma_f32_16x16x32_bf16 v[34:37], v[188:191], v[218:221], v[34:37]
	v_mfma_f32_16x16x32_bf16 v[26:29], v[180:183], v[226:229], v[26:29]
	v_mfma_f32_16x16x32_bf16 v[18:21], v[188:191], v[226:229], v[18:21]
	v_mfma_f32_16x16x32_bf16 v[10:13], v[180:183], v[234:237], v[10:13]
	v_mfma_f32_16x16x32_bf16 v[2:5], v[188:191], v[234:237], v[2:5]
	v_mfma_f32_16x16x32_bf16 v[58:61], v[184:187], v[214:217], v[58:61]
	v_mfma_f32_16x16x32_bf16 v[50:53], v[192:195], v[214:217], v[50:53]
	v_mfma_f32_16x16x32_bf16 v[42:45], v[184:187], v[222:225], v[42:45]
	v_mfma_f32_16x16x32_bf16 v[34:37], v[192:195], v[222:225], v[34:37]
	v_mfma_f32_16x16x32_bf16 v[26:29], v[184:187], v[230:233], v[26:29]
	v_mfma_f32_16x16x32_bf16 v[18:21], v[192:195], v[230:233], v[18:21]
	v_mfma_f32_16x16x32_bf16 v[10:13], v[184:187], v[238:241], v[10:13]
	v_mfma_f32_16x16x32_bf16 v[2:5], v[192:195], v[238:241], v[2:5]
	s_setprio 0
	s_barrier
; __device__ __forceinline__ float row_rstd(const float* rsp, int row, int fq) {
;     const f32x4 v = *(const f32x4*)(rsp + (size_t)row * 16 + 4 * fq);
;     float s = (v[0] + v[1]) + (v[2] + v[3]); s += __shfl_xor(s, 16); s += __shfl_xor(s, 32);
;     return rsqrtf(s * (1.0f / 1024.0f) + RMS_EPS);
;     __device__ __forceinline__ void operator()(const f32x4 (&acc)[2][2][4][2], const Unit& u, int wr, int wc, int fr, int fq) const {
;         const int row0 = u.pm * BM + wr * 64 + fr, col0 = u.pn * HALF + wc * 32 + 8 * fq;
; #pragma unroll
;         for (int ai = 0; ai < 2; ++ai)
; #pragma unroll
;             for (int m = 0; m < 4; ++m) {
;                 const int row = row0 + ai * HALF + m * 16; const float rs = row_rstd(rsp, row, fq);
;                 const float nrs = -LOG2E * rs, rs2 = rs * rs;
;                 const f32x4 g0 = acc[ai][0][m][0], g1 = acc[ai][0][m][1], u0 = acc[ai][1][m][0], u1 = acc[ai][1][m][1];
;                 const f32x4 a0 = g0 * nrs, a1 = g1 * nrs;
;                 f32x4 e0, e1;
; #pragma unroll
;                 for (int q = 0; q < 4; ++q) { e0[q] = __builtin_amdgcn_exp2f(a0[q]); e1[q] = __builtin_amdgcn_exp2f(a1[q]); }
;                 const f32x4 d0 = e0 + 1.0f, d1 = e1 + 1.0f;
;                 f32x4 r0, r1;
; #pragma unroll
;                 for (int q = 0; q < 4; ++q) { r0[q] = __builtin_amdgcn_rcpf(d0[q]); r1[q] = __builtin_amdgcn_rcpf(d1[q]); }
;                 const f32x4 o0 = ((g0 * u0) * rs2) * r0, o1 = ((g1 * u1) * rs2) * r1;
	s_add_i32 s50, s50, 2
	s_add_u32 s22, s22, 0x100
	s_addc_u32 s23, s23, 0
	s_add_u32 s48, s48, 0x100
	s_addc_u32 s49, s49, 0
	s_cmp_gt_u32 s50, 13
	s_cbranch_scc0 .LBB0_493
	v_lshl_add_u32 v142, s45, 8, v148
	v_mov_b32_e32 v143, 0
	s_mov_b32 s26, 0x2000
	s_mov_b32 s27, 0
	v_lshlrev_b64 v[146:147], 6, v[142:143]
	v_lshl_add_u64 v[146:147], v[136:137], 0, v[146:147]
	v_lshl_add_u64 v[156:157], v[146:147], 0, s[26:27]
	global_load_dwordx4 v[172:175], v[146:147], off
	global_load_dwordx4 v[176:179], v[146:147], off offset:1024
	global_load_dwordx4 v[180:183], v[146:147], off offset:2048
	global_load_dwordx4 v[184:187], v[146:147], off offset:3072
	global_load_dwordx4 v[188:191], v[156:157], off
	global_load_dwordx4 v[192:195], v[156:157], off offset:1024
	global_load_dwordx4 v[196:199], v[156:157], off offset:2048
	global_load_dwordx4 v[214:217], v[156:157], off offset:3072
	v_xor_b32_e32 v152, 16, v201
	v_xor_b32_e32 v153, 32, v201
	v_lshlrev_b32_e32 v152, 2, v152
	v_lshlrev_b32_e32 v153, 2, v153
	v_lshl_or_b32 v144, s44, 7, v150
	v_mov_b32_e32 v145, 0
	v_mov_b32_e32 v238, s0
	v_mov_b32_e32 v239, s1
	v_mad_i64_i32 v[236:237], s[22:23], v142, s93, v[238:239]
	v_lshlrev_b64 v[240:241], 1, v[144:145]
	v_mov_b32_e32 v234, 1.0
	v_mov_b32_e32 v235, 1.0
	v_lshl_add_u64 v[236:237], v[236:237], 0, v[240:241]
	s_mov_b32 s26, 0x16000
	s_mov_b32 s24, 0x6e000
	s_mov_b32 s25, 0
	v_pk_mul_f32 v[122:123], v[126:127], v[122:123]
	v_pk_mul_f32 v[124:125], v[128:129], v[124:125]
	v_pk_mul_f32 v[114:115], v[118:119], v[114:115]
	v_pk_mul_f32 v[116:117], v[120:121], v[116:117]
	v_pk_mul_f32 v[106:107], v[110:111], v[106:107]
	v_pk_mul_f32 v[108:109], v[112:113], v[108:109]
	v_pk_mul_f32 v[98:99], v[102:103], v[98:99]
	v_pk_mul_f32 v[100:101], v[104:105], v[100:101]
	v_pk_mul_f32 v[90:91], v[94:95], v[90:91]
	v_pk_mul_f32 v[92:93], v[96:97], v[92:93]
	v_pk_mul_f32 v[82:83], v[86:87], v[82:83]
	v_pk_mul_f32 v[84:85], v[88:89], v[84:85]
	v_pk_mul_f32 v[74:75], v[78:79], v[74:75]
	v_pk_mul_f32 v[76:77], v[80:81], v[76:77]
	v_pk_mul_f32 v[66:67], v[70:71], v[66:67]
	v_pk_mul_f32 v[68:69], v[72:73], v[68:69]
	v_pk_mul_f32 v[58:59], v[62:63], v[58:59]
	v_pk_mul_f32 v[60:61], v[64:65], v[60:61]
	v_pk_mul_f32 v[50:51], v[54:55], v[50:51]
	v_pk_mul_f32 v[52:53], v[56:57], v[52:53]
	v_pk_mul_f32 v[42:43], v[46:47], v[42:43]
	v_pk_mul_f32 v[44:45], v[48:49], v[44:45]
	v_pk_mul_f32 v[34:35], v[38:39], v[34:35]
	v_pk_mul_f32 v[36:37], v[40:41], v[36:37]
	v_pk_mul_f32 v[26:27], v[30:31], v[26:27]
	v_pk_mul_f32 v[28:29], v[32:33], v[28:29]
	v_pk_mul_f32 v[18:19], v[22:23], v[18:19]
	v_pk_mul_f32 v[20:21], v[24:25], v[20:21]
	v_pk_mul_f32 v[10:11], v[14:15], v[10:11]
	v_pk_mul_f32 v[12:13], v[16:17], v[12:13]
	v_pk_mul_f32 v[2:3], v[6:7], v[2:3]
	v_pk_mul_f32 v[4:5], v[8:9], v[4:5]
	s_and_b64 vcc, exec, s[12:13]
	s_cbranch_vccz .LBB0_496
	s_barrier
.LBB0_496:
	s_waitcnt vmcnt(0)
	v_add_f32_e32 v172, v172, v173
	v_add_f32_e32 v176, v176, v177
	v_add_f32_e32 v180, v180, v181
	v_add_f32_e32 v184, v184, v185
	v_add_f32_e32 v188, v188, v189
	v_add_f32_e32 v192, v192, v193
	v_add_f32_e32 v196, v196, v197
	v_add_f32_e32 v214, v214, v215
	v_add_f32_e32 v174, v174, v175
	v_add_f32_e32 v178, v178, v179
	v_add_f32_e32 v182, v182, v183
	v_add_f32_e32 v186, v186, v187
	v_add_f32_e32 v190, v190, v191
	v_add_f32_e32 v194, v194, v195
	v_add_f32_e32 v198, v198, v199
	v_add_f32_e32 v216, v216, v217
	v_add_f32_e32 v172, v172, v174
	v_add_f32_e32 v176, v176, v178
	v_add_f32_e32 v180, v180, v182
	v_add_f32_e32 v184, v184, v186
	v_add_f32_e32 v188, v188, v190
	v_add_f32_e32 v192, v192, v194
	v_add_f32_e32 v196, v196, v198
	v_add_f32_e32 v214, v214, v216
	ds_bpermute_b32 v173, v152, v172
	ds_bpermute_b32 v177, v152, v176
	ds_bpermute_b32 v181, v152, v180
	ds_bpermute_b32 v185, v152, v184
	ds_bpermute_b32 v189, v152, v188
	ds_bpermute_b32 v193, v152, v192
	ds_bpermute_b32 v197, v152, v196
	ds_bpermute_b32 v215, v152, v214
	s_waitcnt lgkmcnt(0)
	v_add_f32_e32 v172, v172, v173
	v_add_f32_e32 v176, v176, v177
	v_add_f32_e32 v180, v180, v181
	v_add_f32_e32 v184, v184, v185
	v_add_f32_e32 v188, v188, v189
	v_add_f32_e32 v192, v192, v193
	v_add_f32_e32 v196, v196, v197
	v_add_f32_e32 v214, v214, v215
	ds_bpermute_b32 v173, v153, v172
	ds_bpermute_b32 v177, v153, v176
	ds_bpermute_b32 v181, v153, v180
	ds_bpermute_b32 v185, v153, v184
	ds_bpermute_b32 v189, v153, v188
	ds_bpermute_b32 v193, v153, v192
	ds_bpermute_b32 v197, v153, v196
	ds_bpermute_b32 v215, v153, v214
	s_waitcnt lgkmcnt(0)
; __device__ __forceinline__ unsigned cvt_pk_bf16(float lo, float hi) { f32x2_cv v = {lo, hi}; bf16x2_cv b = __builtin_convertvector(v, bf16x2_cv); return __builtin_bit_cast(unsigned, b); }
; __device__ __forceinline__ float row_rstd(const float* rsp, int row, int fq) {
;     const f32x4 v = *(const f32x4*)(rsp + (size_t)row * 16 + 4 * fq);
;     float s = (v[0] + v[1]) + (v[2] + v[3]); s += __shfl_xor(s, 16); s += __shfl_xor(s, 32);
;     return rsqrtf(s * (1.0f / 1024.0f) + RMS_EPS);
;     __device__ __forceinline__ void operator()(const f32x4 (&acc)[2][2][4][2], const Unit& u, int wr, int wc, int fr, int fq) const {
;     ...
;                 const int row = row0 + ai * HALF + m * 16; const float rs = row_rstd(rsp, row, fq);
;                 const float nrs = -LOG2E * rs, rs2 = rs * rs;
;                 const f32x4 g0 = acc[ai][0][m][0], g1 = acc[ai][0][m][1], u0 = acc[ai][1][m][0], u1 = acc[ai][1][m][1];
;                 const f32x4 a0 = g0 * nrs, a1 = g1 * nrs;
;                 f32x4 e0, e1;
; #pragma unroll
;                 for (int q = 0; q < 4; ++q) { e0[q] = __builtin_amdgcn_exp2f(a0[q]); e1[q] = __builtin_amdgcn_exp2f(a1[q]); }
;                 const f32x4 d0 = e0 + 1.0f, d1 = e1 + 1.0f;
;                 f32x4 r0, r1;
; #pragma unroll
;                 for (int q = 0; q < 4; ++q) { r0[q] = __builtin_amdgcn_rcpf(d0[q]); r1[q] = __builtin_amdgcn_rcpf(d1[q]); }
;                 const f32x4 o0 = ((g0 * u0) * rs2) * r0, o1 = ((g1 * u1) * rs2) * r1;
;                 u32x4 w; w.x = cvt_pk_bf16(o0[0], o0[1]); w.y = cvt_pk_bf16(o0[2], o0[3]); w.z = cvt_pk_bf16(o1[0], o1[1]); w.w = cvt_pk_bf16(o1[2], o1[3]);
;                 *(u32x4*)(O + (size_t)row * ldc + col0) = w;
	v_add_f32_e32 v172, v172, v173
	v_add_f32_e32 v176, v176, v177
	v_add_f32_e32 v180, v180, v181
	v_add_f32_e32 v184, v184, v185
	v_add_f32_e32 v188, v188, v189
	v_add_f32_e32 v192, v192, v193
	v_add_f32_e32 v196, v196, v197
	v_add_f32_e32 v214, v214, v215
	v_fmamk_f32 v172, v172, 0x3a800000, v207
	v_fmamk_f32 v176, v176, 0x3a800000, v207
	v_fmamk_f32 v180, v180, 0x3a800000, v207
	v_fmamk_f32 v184, v184, 0x3a800000, v207
	v_fmamk_f32 v188, v188, 0x3a800000, v207
	v_fmamk_f32 v192, v192, 0x3a800000, v207
	v_fmamk_f32 v196, v196, 0x3a800000, v207
	v_fmamk_f32 v214, v214, 0x3a800000, v207
	v_rsq_f32_e32 v172, v172
	v_rsq_f32_e32 v176, v176
	v_rsq_f32_e32 v180, v180
	v_rsq_f32_e32 v184, v184
	v_rsq_f32_e32 v188, v188
	v_rsq_f32_e32 v192, v192
	v_rsq_f32_e32 v196, v196
	v_rsq_f32_e32 v214, v214
	v_mul_f32_e32 v174, v172, v172
	v_mul_f32_e32 v178, v176, v176
	v_mul_f32_e32 v182, v180, v180
	v_mul_f32_e32 v186, v184, v184
	v_mul_f32_e32 v190, v188, v188
	v_mul_f32_e32 v194, v192, v192
	v_mul_f32_e32 v198, v196, v196
	v_mul_f32_e32 v216, v214, v214
	v_mul_f32_e32 v172, 0xbfb8aa3b, v172
	v_mul_f32_e32 v176, 0xbfb8aa3b, v176
	v_mul_f32_e32 v180, 0xbfb8aa3b, v180
	v_mul_f32_e32 v184, 0xbfb8aa3b, v184
	v_mul_f32_e32 v188, 0xbfb8aa3b, v188
	v_mul_f32_e32 v192, 0xbfb8aa3b, v192
	v_mul_f32_e32 v196, 0xbfb8aa3b, v196
	v_mul_f32_e32 v214, 0xbfb8aa3b, v214
	v_pk_mul_f32 v[218:219], v[126:127], v[172:173] op_sel_hi:[1,0]
	v_pk_mul_f32 v[220:221], v[128:129], v[172:173] op_sel_hi:[1,0]
	v_pk_mul_f32 v[222:223], v[118:119], v[172:173] op_sel_hi:[1,0]
	v_pk_mul_f32 v[224:225], v[120:121], v[172:173] op_sel_hi:[1,0]
	v_exp_f32_e32 v218, v218
	v_exp_f32_e32 v219, v219
	v_exp_f32_e32 v220, v220
	v_exp_f32_e32 v221, v221
	v_exp_f32_e32 v222, v222
	v_exp_f32_e32 v223, v223
	v_exp_f32_e32 v224, v224
	v_exp_f32_e32 v225, v225
	v_pk_add_f32 v[218:219], v[218:219], v[234:235]
	v_pk_add_f32 v[220:221], v[220:221], v[234:235]
	v_pk_add_f32 v[222:223], v[222:223], v[234:235]
	v_pk_add_f32 v[224:225], v[224:225], v[234:235]
	v_rcp_f32_e32 v218, v218
	v_rcp_f32_e32 v219, v219
	v_rcp_f32_e32 v220, v220
	v_rcp_f32_e32 v221, v221
	v_rcp_f32_e32 v222, v222
	v_rcp_f32_e32 v223, v223
	v_rcp_f32_e32 v224, v224
	v_rcp_f32_e32 v225, v225
	v_pk_mul_f32 v[122:123], v[122:123], v[174:175] op_sel_hi:[1,0]
	v_pk_mul_f32 v[124:125], v[124:125], v[174:175] op_sel_hi:[1,0]
	v_pk_mul_f32 v[114:115], v[114:115], v[174:175] op_sel_hi:[1,0]
	v_pk_mul_f32 v[116:117], v[116:117], v[174:175] op_sel_hi:[1,0]
	v_pk_mul_f32 v[122:123], v[122:123], v[218:219]
	v_pk_mul_f32 v[124:125], v[124:125], v[220:221]
	v_pk_mul_f32 v[114:115], v[114:115], v[222:223]
	v_pk_mul_f32 v[116:117], v[116:117], v[224:225]
	v_cvt_pk_bf16_f32 v118, v122, v123
	v_cvt_pk_bf16_f32 v119, v124, v125
	v_cvt_pk_bf16_f32 v120, v114, v115
	v_cvt_pk_bf16_f32 v121, v116, v117
	global_store_dwordx4 v[236:237], v[118:121], off
	v_lshl_add_u64 v[236:237], v[236:237], 0, s[26:27]
	v_pk_mul_f32 v[226:227], v[110:111], v[176:177] op_sel_hi:[1,0]
	v_pk_mul_f32 v[228:229], v[112:113], v[176:177] op_sel_hi:[1,0]
	v_pk_mul_f32 v[230:231], v[102:103], v[176:177] op_sel_hi:[1,0]
	v_pk_mul_f32 v[232:233], v[104:105], v[176:177] op_sel_hi:[1,0]
	v_exp_f32_e32 v226, v226
	v_exp_f32_e32 v227, v227
	v_exp_f32_e32 v228, v228
	v_exp_f32_e32 v229, v229
	v_exp_f32_e32 v230, v230
	v_exp_f32_e32 v231, v231
	v_exp_f32_e32 v232, v232
	v_exp_f32_e32 v233, v233
	v_pk_add_f32 v[226:227], v[226:227], v[234:235]
	v_pk_add_f32 v[228:229], v[228:229], v[234:235]
	v_pk_add_f32 v[230:231], v[230:231], v[234:235]
	v_pk_add_f32 v[232:233], v[232:233], v[234:235]
	v_rcp_f32_e32 v226, v226
	v_rcp_f32_e32 v227, v227
	v_rcp_f32_e32 v228, v228
	v_rcp_f32_e32 v229, v229
	v_rcp_f32_e32 v230, v230
	v_rcp_f32_e32 v231, v231
	v_rcp_f32_e32 v232, v232
	v_rcp_f32_e32 v233, v233
	v_pk_mul_f32 v[106:107], v[106:107], v[178:179] op_sel_hi:[1,0]
	v_pk_mul_f32 v[108:109], v[108:109], v[178:179] op_sel_hi:[1,0]
	v_pk_mul_f32 v[98:99], v[98:99], v[178:179] op_sel_hi:[1,0]
	v_pk_mul_f32 v[100:101], v[100:101], v[178:179] op_sel_hi:[1,0]
	v_pk_mul_f32 v[106:107], v[106:107], v[226:227]
	v_pk_mul_f32 v[108:109], v[108:109], v[228:229]
	v_pk_mul_f32 v[98:99], v[98:99], v[230:231]
	v_pk_mul_f32 v[100:101], v[100:101], v[232:233]
	v_cvt_pk_bf16_f32 v102, v106, v107
	v_cvt_pk_bf16_f32 v103, v108, v109
	v_cvt_pk_bf16_f32 v104, v98, v99
	v_cvt_pk_bf16_f32 v105, v100, v101
	global_store_dwordx4 v[236:237], v[102:105], off
	v_lshl_add_u64 v[236:237], v[236:237], 0, s[26:27]
	v_pk_mul_f32 v[218:219], v[94:95], v[180:181] op_sel_hi:[1,0]
	v_pk_mul_f32 v[220:221], v[96:97], v[180:181] op_sel_hi:[1,0]
	v_pk_mul_f32 v[222:223], v[86:87], v[180:181] op_sel_hi:[1,0]
	v_pk_mul_f32 v[224:225], v[88:89], v[180:181] op_sel_hi:[1,0]
	v_exp_f32_e32 v218, v218
	v_exp_f32_e32 v219, v219
	v_exp_f32_e32 v220, v220
	v_exp_f32_e32 v221, v221
	v_exp_f32_e32 v222, v222
	v_exp_f32_e32 v223, v223
	v_exp_f32_e32 v224, v224
	v_exp_f32_e32 v225, v225
	v_pk_add_f32 v[218:219], v[218:219], v[234:235]
	v_pk_add_f32 v[220:221], v[220:221], v[234:235]
	v_pk_add_f32 v[222:223], v[222:223], v[234:235]
	v_pk_add_f32 v[224:225], v[224:225], v[234:235]
	v_rcp_f32_e32 v218, v218
	v_rcp_f32_e32 v219, v219
	v_rcp_f32_e32 v220, v220
	v_rcp_f32_e32 v221, v221
	v_rcp_f32_e32 v222, v222
	v_rcp_f32_e32 v223, v223
	v_rcp_f32_e32 v224, v224
	v_rcp_f32_e32 v225, v225
	v_pk_mul_f32 v[90:91], v[90:91], v[182:183] op_sel_hi:[1,0]
	v_pk_mul_f32 v[92:93], v[92:93], v[182:183] op_sel_hi:[1,0]
	v_pk_mul_f32 v[82:83], v[82:83], v[182:183] op_sel_hi:[1,0]
	v_pk_mul_f32 v[84:85], v[84:85], v[182:183] op_sel_hi:[1,0]
	v_pk_mul_f32 v[90:91], v[90:91], v[218:219]
; __device__ __forceinline__ unsigned cvt_pk_bf16(float lo, float hi) { f32x2_cv v = {lo, hi}; bf16x2_cv b = __builtin_convertvector(v, bf16x2_cv); return __builtin_bit_cast(unsigned, b); }
;     __device__ __forceinline__ void operator()(const f32x4 (&acc)[2][2][4][2], const Unit& u, int wr, int wc, int fr, int fq) const {
;     ...
;                 const int row = row0 + ai * HALF + m * 16; const float rs = row_rstd(rsp, row, fq);
;                 const float nrs = -LOG2E * rs, rs2 = rs * rs;
;                 const f32x4 g0 = acc[ai][0][m][0], g1 = acc[ai][0][m][1], u0 = acc[ai][1][m][0], u1 = acc[ai][1][m][1];
;                 const f32x4 a0 = g0 * nrs, a1 = g1 * nrs;
;                 f32x4 e0, e1;
; #pragma unroll
;                 for (int q = 0; q < 4; ++q) { e0[q] = __builtin_amdgcn_exp2f(a0[q]); e1[q] = __builtin_amdgcn_exp2f(a1[q]); }
;                 const f32x4 d0 = e0 + 1.0f, d1 = e1 + 1.0f;
;                 f32x4 r0, r1;
; #pragma unroll
;                 for (int q = 0; q < 4; ++q) { r0[q] = __builtin_amdgcn_rcpf(d0[q]); r1[q] = __builtin_amdgcn_rcpf(d1[q]); }
;                 const f32x4 o0 = ((g0 * u0) * rs2) * r0, o1 = ((g1 * u1) * rs2) * r1;
;                 u32x4 w; w.x = cvt_pk_bf16(o0[0], o0[1]); w.y = cvt_pk_bf16(o0[2], o0[3]); w.z = cvt_pk_bf16(o1[0], o1[1]); w.w = cvt_pk_bf16(o1[2], o1[3]);
;                 *(u32x4*)(O + (size_t)row * ldc + col0) = w;
	v_pk_mul_f32 v[92:93], v[92:93], v[220:221]
	v_pk_mul_f32 v[82:83], v[82:83], v[222:223]
	v_pk_mul_f32 v[84:85], v[84:85], v[224:225]
	v_cvt_pk_bf16_f32 v86, v90, v91
	v_cvt_pk_bf16_f32 v87, v92, v93
	v_cvt_pk_bf16_f32 v88, v82, v83
	v_cvt_pk_bf16_f32 v89, v84, v85
	global_store_dwordx4 v[236:237], v[86:89], off
	v_lshl_add_u64 v[236:237], v[236:237], 0, s[26:27]
	v_pk_mul_f32 v[226:227], v[78:79], v[184:185] op_sel_hi:[1,0]
	v_pk_mul_f32 v[228:229], v[80:81], v[184:185] op_sel_hi:[1,0]
	v_pk_mul_f32 v[230:231], v[70:71], v[184:185] op_sel_hi:[1,0]
	v_pk_mul_f32 v[232:233], v[72:73], v[184:185] op_sel_hi:[1,0]
	v_exp_f32_e32 v226, v226
	v_exp_f32_e32 v227, v227
	v_exp_f32_e32 v228, v228
	v_exp_f32_e32 v229, v229
	v_exp_f32_e32 v230, v230
	v_exp_f32_e32 v231, v231
	v_exp_f32_e32 v232, v232
	v_exp_f32_e32 v233, v233
	v_pk_add_f32 v[226:227], v[226:227], v[234:235]
	v_pk_add_f32 v[228:229], v[228:229], v[234:235]
	v_pk_add_f32 v[230:231], v[230:231], v[234:235]
	v_pk_add_f32 v[232:233], v[232:233], v[234:235]
	v_rcp_f32_e32 v226, v226
	v_rcp_f32_e32 v227, v227
	v_rcp_f32_e32 v228, v228
	v_rcp_f32_e32 v229, v229
	v_rcp_f32_e32 v230, v230
	v_rcp_f32_e32 v231, v231
	v_rcp_f32_e32 v232, v232
	v_rcp_f32_e32 v233, v233
	v_pk_mul_f32 v[74:75], v[74:75], v[186:187] op_sel_hi:[1,0]
	v_pk_mul_f32 v[76:77], v[76:77], v[186:187] op_sel_hi:[1,0]
	v_pk_mul_f32 v[66:67], v[66:67], v[186:187] op_sel_hi:[1,0]
	v_pk_mul_f32 v[68:69], v[68:69], v[186:187] op_sel_hi:[1,0]
	v_pk_mul_f32 v[74:75], v[74:75], v[226:227]
	v_pk_mul_f32 v[76:77], v[76:77], v[228:229]
	v_pk_mul_f32 v[66:67], v[66:67], v[230:231]
	v_pk_mul_f32 v[68:69], v[68:69], v[232:233]
	v_cvt_pk_bf16_f32 v70, v74, v75
	v_cvt_pk_bf16_f32 v71, v76, v77
	v_cvt_pk_bf16_f32 v72, v66, v67
	v_cvt_pk_bf16_f32 v73, v68, v69
	global_store_dwordx4 v[236:237], v[70:73], off
	v_lshl_add_u64 v[236:237], v[236:237], 0, s[24:25]
	v_pk_mul_f32 v[218:219], v[62:63], v[188:189] op_sel_hi:[1,0]
	v_pk_mul_f32 v[220:221], v[64:65], v[188:189] op_sel_hi:[1,0]
	v_pk_mul_f32 v[222:223], v[54:55], v[188:189] op_sel_hi:[1,0]
	v_pk_mul_f32 v[224:225], v[56:57], v[188:189] op_sel_hi:[1,0]
	v_exp_f32_e32 v218, v218
	v_exp_f32_e32 v219, v219
	v_exp_f32_e32 v220, v220
	v_exp_f32_e32 v221, v221
	v_exp_f32_e32 v222, v222
	v_exp_f32_e32 v223, v223
	v_exp_f32_e32 v224, v224
	v_exp_f32_e32 v225, v225
	v_pk_add_f32 v[218:219], v[218:219], v[234:235]
	v_pk_add_f32 v[220:221], v[220:221], v[234:235]
	v_pk_add_f32 v[222:223], v[222:223], v[234:235]
	v_pk_add_f32 v[224:225], v[224:225], v[234:235]
	v_rcp_f32_e32 v218, v218
	v_rcp_f32_e32 v219, v219
	v_rcp_f32_e32 v220, v220
	v_rcp_f32_e32 v221, v221
	v_rcp_f32_e32 v222, v222
	v_rcp_f32_e32 v223, v223
	v_rcp_f32_e32 v224, v224
	v_rcp_f32_e32 v225, v225
	v_pk_mul_f32 v[58:59], v[58:59], v[190:191] op_sel_hi:[1,0]
	v_pk_mul_f32 v[60:61], v[60:61], v[190:191] op_sel_hi:[1,0]
	v_pk_mul_f32 v[50:51], v[50:51], v[190:191] op_sel_hi:[1,0]
	v_pk_mul_f32 v[52:53], v[52:53], v[190:191] op_sel_hi:[1,0]
	v_pk_mul_f32 v[58:59], v[58:59], v[218:219]
	v_pk_mul_f32 v[60:61], v[60:61], v[220:221]
	v_pk_mul_f32 v[50:51], v[50:51], v[222:223]
	v_pk_mul_f32 v[52:53], v[52:53], v[224:225]
	v_cvt_pk_bf16_f32 v54, v58, v59
	v_cvt_pk_bf16_f32 v55, v60, v61
	v_cvt_pk_bf16_f32 v56, v50, v51
	v_cvt_pk_bf16_f32 v57, v52, v53
	global_store_dwordx4 v[236:237], v[54:57], off
	v_lshl_add_u64 v[236:237], v[236:237], 0, s[26:27]
	v_pk_mul_f32 v[226:227], v[46:47], v[192:193] op_sel_hi:[1,0]
	v_pk_mul_f32 v[228:229], v[48:49], v[192:193] op_sel_hi:[1,0]
	v_pk_mul_f32 v[230:231], v[38:39], v[192:193] op_sel_hi:[1,0]
	v_pk_mul_f32 v[232:233], v[40:41], v[192:193] op_sel_hi:[1,0]
	v_exp_f32_e32 v226, v226
	v_exp_f32_e32 v227, v227
	v_exp_f32_e32 v228, v228
	v_exp_f32_e32 v229, v229
	v_exp_f32_e32 v230, v230
	v_exp_f32_e32 v231, v231
	v_exp_f32_e32 v232, v232
	v_exp_f32_e32 v233, v233
	v_pk_add_f32 v[226:227], v[226:227], v[234:235]
	v_pk_add_f32 v[228:229], v[228:229], v[234:235]
	v_pk_add_f32 v[230:231], v[230:231], v[234:235]
; __device__ __forceinline__ unsigned cvt_pk_bf16(float lo, float hi) { f32x2_cv v = {lo, hi}; bf16x2_cv b = __builtin_convertvector(v, bf16x2_cv); return __builtin_bit_cast(unsigned, b); }
; #define PG8_BAR __builtin_amdgcn_s_barrier()
; template <class Epi, class Sched, bool ALIGN_EPI = false, bool SP2 = false>
; __device__ __forceinline__ void gemm_phase(PG8_LAS unsigned char* lds, const Gemm g, const Sched& S, const Epi& E) {
;     ...
;         if (!has_next) break;
; #pragma unroll
;         for (int a = 0; a < 2; ++a)
; #pragma unroll
;             for (int b = 0; b < 2; ++b)
; #pragma unroll
;                 for (int m = 0; m < 4; ++m)
; #pragma unroll
;                     for (int n = 0; n < 2; ++n) acc[a][b][m][n] = (f32x4){0.f, 0.f, 0.f, 0.f};
;         cur = nxt; cA = nA; cB = nB; ++ui;
;         if constexpr (ALIGN_EPI) { if (wr == 1) PG8_BAR; }
;     __device__ __forceinline__ void operator()(const f32x4 (&acc)[2][2][4][2], const Unit& u, int wr, int wc, int fr, int fq) const {
;     ...
;                 const int row = row0 + ai * HALF + m * 16; const float rs = row_rstd(rsp, row, fq);
;                 const float nrs = -LOG2E * rs, rs2 = rs * rs;
;                 const f32x4 g0 = acc[ai][0][m][0], g1 = acc[ai][0][m][1], u0 = acc[ai][1][m][0], u1 = acc[ai][1][m][1];
;                 const f32x4 a0 = g0 * nrs, a1 = g1 * nrs;
;                 f32x4 e0, e1;
; #pragma unroll
;                 for (int q = 0; q < 4; ++q) { e0[q] = __builtin_amdgcn_exp2f(a0[q]); e1[q] = __builtin_amdgcn_exp2f(a1[q]); }
;                 const f32x4 d0 = e0 + 1.0f, d1 = e1 + 1.0f;
;                 f32x4 r0, r1;
; #pragma unroll
;                 for (int q = 0; q < 4; ++q) { r0[q] = __builtin_amdgcn_rcpf(d0[q]); r1[q] = __builtin_amdgcn_rcpf(d1[q]); }
;                 const f32x4 o0 = ((g0 * u0) * rs2) * r0, o1 = ((g1 * u1) * rs2) * r1;
;                 u32x4 w; w.x = cvt_pk_bf16(o0[0], o0[1]); w.y = cvt_pk_bf16(o0[2], o0[3]); w.z = cvt_pk_bf16(o1[0], o1[1]); w.w = cvt_pk_bf16(o1[2], o1[3]);
;                 *(u32x4*)(O + (size_t)row * ldc + col0) = w;
	v_pk_add_f32 v[232:233], v[232:233], v[234:235]
	v_rcp_f32_e32 v226, v226
	v_rcp_f32_e32 v227, v227
	v_rcp_f32_e32 v228, v228
	v_rcp_f32_e32 v229, v229
	v_rcp_f32_e32 v230, v230
	v_rcp_f32_e32 v231, v231
	v_rcp_f32_e32 v232, v232
	v_rcp_f32_e32 v233, v233
	v_pk_mul_f32 v[42:43], v[42:43], v[194:195] op_sel_hi:[1,0]
	v_pk_mul_f32 v[44:45], v[44:45], v[194:195] op_sel_hi:[1,0]
	v_pk_mul_f32 v[34:35], v[34:35], v[194:195] op_sel_hi:[1,0]
	v_pk_mul_f32 v[36:37], v[36:37], v[194:195] op_sel_hi:[1,0]
	v_pk_mul_f32 v[42:43], v[42:43], v[226:227]
	v_pk_mul_f32 v[44:45], v[44:45], v[228:229]
	v_pk_mul_f32 v[34:35], v[34:35], v[230:231]
	v_pk_mul_f32 v[36:37], v[36:37], v[232:233]
	v_cvt_pk_bf16_f32 v38, v42, v43
	v_cvt_pk_bf16_f32 v39, v44, v45
	v_cvt_pk_bf16_f32 v40, v34, v35
	v_cvt_pk_bf16_f32 v41, v36, v37
	global_store_dwordx4 v[236:237], v[38:41], off
	v_lshl_add_u64 v[236:237], v[236:237], 0, s[26:27]
	v_pk_mul_f32 v[218:219], v[30:31], v[196:197] op_sel_hi:[1,0]
	v_pk_mul_f32 v[220:221], v[32:33], v[196:197] op_sel_hi:[1,0]
	v_pk_mul_f32 v[222:223], v[22:23], v[196:197] op_sel_hi:[1,0]
	v_pk_mul_f32 v[224:225], v[24:25], v[196:197] op_sel_hi:[1,0]
	v_exp_f32_e32 v218, v218
	v_exp_f32_e32 v219, v219
	v_exp_f32_e32 v220, v220
	v_exp_f32_e32 v221, v221
	v_exp_f32_e32 v222, v222
	v_exp_f32_e32 v223, v223
	v_exp_f32_e32 v224, v224
	v_exp_f32_e32 v225, v225
	v_pk_add_f32 v[218:219], v[218:219], v[234:235]
	v_pk_add_f32 v[220:221], v[220:221], v[234:235]
	v_pk_add_f32 v[222:223], v[222:223], v[234:235]
	v_pk_add_f32 v[224:225], v[224:225], v[234:235]
	v_rcp_f32_e32 v218, v218
	v_rcp_f32_e32 v219, v219
	v_rcp_f32_e32 v220, v220
	v_rcp_f32_e32 v221, v221
	v_rcp_f32_e32 v222, v222
	v_rcp_f32_e32 v223, v223
	v_rcp_f32_e32 v224, v224
	v_rcp_f32_e32 v225, v225
	v_pk_mul_f32 v[26:27], v[26:27], v[198:199] op_sel_hi:[1,0]
	v_pk_mul_f32 v[28:29], v[28:29], v[198:199] op_sel_hi:[1,0]
	v_pk_mul_f32 v[18:19], v[18:19], v[198:199] op_sel_hi:[1,0]
	v_pk_mul_f32 v[20:21], v[20:21], v[198:199] op_sel_hi:[1,0]
	v_pk_mul_f32 v[26:27], v[26:27], v[218:219]
	v_pk_mul_f32 v[28:29], v[28:29], v[220:221]
	v_pk_mul_f32 v[18:19], v[18:19], v[222:223]
	v_pk_mul_f32 v[20:21], v[20:21], v[224:225]
	v_cvt_pk_bf16_f32 v22, v26, v27
	v_cvt_pk_bf16_f32 v23, v28, v29
	v_cvt_pk_bf16_f32 v24, v18, v19
	v_cvt_pk_bf16_f32 v25, v20, v21
	global_store_dwordx4 v[236:237], v[22:25], off
	v_lshl_add_u64 v[236:237], v[236:237], 0, s[26:27]
	v_pk_mul_f32 v[226:227], v[14:15], v[214:215] op_sel_hi:[1,0]
	v_pk_mul_f32 v[228:229], v[16:17], v[214:215] op_sel_hi:[1,0]
	v_pk_mul_f32 v[230:231], v[6:7], v[214:215] op_sel_hi:[1,0]
	v_pk_mul_f32 v[232:233], v[8:9], v[214:215] op_sel_hi:[1,0]
	v_exp_f32_e32 v226, v226
	v_exp_f32_e32 v227, v227
	v_exp_f32_e32 v228, v228
	v_exp_f32_e32 v229, v229
	v_exp_f32_e32 v230, v230
	v_exp_f32_e32 v231, v231
	v_exp_f32_e32 v232, v232
	v_exp_f32_e32 v233, v233
	v_pk_add_f32 v[226:227], v[226:227], v[234:235]
	v_pk_add_f32 v[228:229], v[228:229], v[234:235]
	v_pk_add_f32 v[230:231], v[230:231], v[234:235]
	v_pk_add_f32 v[232:233], v[232:233], v[234:235]
	v_rcp_f32_e32 v226, v226
	v_rcp_f32_e32 v227, v227
	v_rcp_f32_e32 v228, v228
	v_rcp_f32_e32 v229, v229
	v_rcp_f32_e32 v230, v230
	v_rcp_f32_e32 v231, v231
	v_rcp_f32_e32 v232, v232
	v_rcp_f32_e32 v233, v233
	v_pk_mul_f32 v[10:11], v[10:11], v[216:217] op_sel_hi:[1,0]
	v_pk_mul_f32 v[12:13], v[12:13], v[216:217] op_sel_hi:[1,0]
	v_pk_mul_f32 v[2:3], v[2:3], v[216:217] op_sel_hi:[1,0]
	v_pk_mul_f32 v[4:5], v[4:5], v[216:217] op_sel_hi:[1,0]
	v_pk_mul_f32 v[10:11], v[10:11], v[226:227]
	v_pk_mul_f32 v[12:13], v[12:13], v[228:229]
	v_pk_mul_f32 v[2:3], v[2:3], v[230:231]
	v_pk_mul_f32 v[4:5], v[4:5], v[232:233]
	v_cvt_pk_bf16_f32 v6, v10, v11
	v_cvt_pk_bf16_f32 v7, v12, v13
	v_cvt_pk_bf16_f32 v8, v2, v3
	v_cvt_pk_bf16_f32 v9, v4, v5
	global_store_dwordx4 v[236:237], v[6:9], off
	s_mov_b64 s[22:23], -1
	s_andn2_b64 vcc, exec, s[4:5]
	s_cbranch_vccnz .LBB0_489
	s_andn2_b64 vcc, exec, s[8:9]
	s_cbranch_vccnz .LBB0_488
	s_barrier
	s_branch .LBB0_488
